# phase F SwiGLU epilogue rewritten by hand with packed f32 on column pairs (599 vs 996 instructions, same per-element operations) on top of the mixer LDS-read hoisting
# speedup vs baseline: 1.0080x; 1.0080x over previous
; __device__ __forceinline__ float fast_sigmoid(float x) { return __builtin_amdgcn_rcpf(1.0f + __expf(-x)); }
;     __device__ __forceinline__ void operator()(const i32x4 (&acc)[2][2][4][2], const Unit& u, int wr, int wc, int fr, int fq) const {
;         const int row0 = u.pm * BM + wr * 64 + fr, col0 = u.pn * HALF + wc * 32 + 8 * fq, brow = u.pn * BM + wc * 32 + 8 * fq;
;         const f32x4 dg0 = *(const f32x4*)(DB + brow), dg1 = *(const f32x4*)(DB + brow + 4), du0 = *(const f32x4*)(DB + brow + HALF), du1 = *(const f32x4*)(DB + brow + HALF + 4);
;         float rav[2][4];
; #pragma unroll
;         for (int ai = 0; ai < 2; ++ai)
; #pragma unroll
;             for (int m = 0; m < 4; ++m) rav[ai][m] = RA[row0 + ai * HALF + m * 16];
;         __builtin_amdgcn_sched_barrier(0);
; #pragma unroll
;         for (int ai = 0; ai < 2; ++ai)
; #pragma unroll
;             for (int m = 0; m < 4; ++m) { const int row = row0 + ai * HALF + m * 16; const float ra = rav[ai][m]; bf16_t* rowp = H + (size_t)row * ldh + col0;
;                 float hv[8];
; #pragma unroll
;                 for (int j = 0; j < 4; ++j) { const float g0 = (float)acc[ai][0][m][0][j] * ra * dg0[j], u0 = (float)acc[ai][1][m][0][j] * ra * du0[j]; hv[j] = g0 * fast_sigmoid(g0) * u0;
.LBB0_1594:
	v_lshl_add_u32 v160, s35, 8, v159
	v_lshl_or_b32 v36, s34, 8, v169
	v_or_b32_e32 v178, 32, v160
	v_ashrrev_i32_e32 v37, 31, v36
	v_ashrrev_i32_e32 v161, 31, v160
	v_or_b32_e32 v182, 16, v160
	v_ashrrev_i32_e32 v179, 31, v178
	v_or_b32_e32 v174, 48, v160
	v_lshl_add_u64 v[144:145], v[36:37], 2, s[18:19]
	v_lshl_add_u64 v[162:163], v[160:161], 2, s[16:17]
	v_ashrrev_i32_e32 v183, 31, v182
	v_lshl_add_u64 v[172:173], v[178:179], 2, s[16:17]
	v_ashrrev_i32_e32 v175, 31, v174
	global_load_dwordx4 v[36:39], v[144:145], off offset:16
	global_load_dwordx4 v[44:47], v[144:145], off
	global_load_dwordx4 v[140:143], v[144:145], off offset:528
	s_nop 0
	global_load_dwordx4 v[144:147], v[144:145], off offset:512
	v_lshl_add_u64 v[164:165], v[182:183], 2, s[16:17]
	v_lshl_add_u64 v[184:185], v[174:175], 2, s[16:17]
	global_load_dword v188, v[162:163], off
	global_load_dword v180, v[164:165], off
	global_load_dword v176, v[172:173], off
	s_nop 0
	global_load_dword v172, v[184:185], off
	global_load_dword v170, v[162:163], off offset:512
	global_load_dword v168, v[162:163], off offset:576
	global_load_dword v166, v[162:163], off offset:640
	global_load_dword v158, v[162:163], off offset:704
	v_lshl_or_b32 v186, s34, 7, v169
	s_movk_i32 s23, 0x5600
	v_lshlrev_b32_e32 v186, 1, v186
	v_mad_u32_u24 v186, v160, s23, v186
	v_mov_b32_e32 v178, 0xbfb8aa3b
	v_mov_b32_e32 v179, 1.0
	v_cvt_f32_i32_e32 v136, v136
	v_cvt_f32_i32_e32 v137, v137
	v_cvt_f32_i32_e32 v138, v138
	v_cvt_f32_i32_e32 v139, v139
	v_cvt_f32_i32_e32 v132, v132
	v_cvt_f32_i32_e32 v133, v133
	v_cvt_f32_i32_e32 v134, v134
	v_cvt_f32_i32_e32 v135, v135
	v_cvt_f32_i32_e32 v128, v128
	v_cvt_f32_i32_e32 v129, v129
	v_cvt_f32_i32_e32 v130, v130
	v_cvt_f32_i32_e32 v131, v131
	v_cvt_f32_i32_e32 v124, v124
	v_cvt_f32_i32_e32 v125, v125
	v_cvt_f32_i32_e32 v126, v126
	v_cvt_f32_i32_e32 v127, v127
	v_cvt_f32_i32_e32 v120, v120
	v_cvt_f32_i32_e32 v121, v121
	v_cvt_f32_i32_e32 v122, v122
	v_cvt_f32_i32_e32 v123, v123
	v_cvt_f32_i32_e32 v116, v116
	v_cvt_f32_i32_e32 v117, v117
	v_cvt_f32_i32_e32 v118, v118
	v_cvt_f32_i32_e32 v119, v119
	v_cvt_f32_i32_e32 v112, v112
	v_cvt_f32_i32_e32 v113, v113
	v_cvt_f32_i32_e32 v114, v114
	v_cvt_f32_i32_e32 v115, v115
	v_cvt_f32_i32_e32 v108, v108
	v_cvt_f32_i32_e32 v109, v109
	v_cvt_f32_i32_e32 v110, v110
	v_cvt_f32_i32_e32 v111, v111
	v_cvt_f32_i32_e32 v104, v104
	v_cvt_f32_i32_e32 v105, v105
	v_cvt_f32_i32_e32 v106, v106
	v_cvt_f32_i32_e32 v107, v107
	v_cvt_f32_i32_e32 v100, v100
	v_cvt_f32_i32_e32 v101, v101
	v_cvt_f32_i32_e32 v102, v102
	v_cvt_f32_i32_e32 v103, v103
	v_cvt_f32_i32_e32 v96, v96
	v_cvt_f32_i32_e32 v97, v97
	v_cvt_f32_i32_e32 v98, v98
	v_cvt_f32_i32_e32 v99, v99
	v_cvt_f32_i32_e32 v92, v92
	v_cvt_f32_i32_e32 v93, v93
	v_cvt_f32_i32_e32 v94, v94
	v_cvt_f32_i32_e32 v95, v95
	v_cvt_f32_i32_e32 v88, v88
	v_cvt_f32_i32_e32 v89, v89
	v_cvt_f32_i32_e32 v90, v90
	v_cvt_f32_i32_e32 v91, v91
	v_cvt_f32_i32_e32 v84, v84
	v_cvt_f32_i32_e32 v85, v85
	v_cvt_f32_i32_e32 v86, v86
	v_cvt_f32_i32_e32 v87, v87
	v_cvt_f32_i32_e32 v80, v80
	v_cvt_f32_i32_e32 v81, v81
	v_cvt_f32_i32_e32 v82, v82
	v_cvt_f32_i32_e32 v83, v83
	v_cvt_f32_i32_e32 v76, v76
	v_cvt_f32_i32_e32 v77, v77
	v_cvt_f32_i32_e32 v78, v78
	v_cvt_f32_i32_e32 v79, v79
	v_cvt_f32_i32_e32 v72, v72
	v_cvt_f32_i32_e32 v73, v73
	v_cvt_f32_i32_e32 v74, v74
	v_cvt_f32_i32_e32 v75, v75
	v_cvt_f32_i32_e32 v68, v68
	v_cvt_f32_i32_e32 v69, v69
	v_cvt_f32_i32_e32 v70, v70
	v_cvt_f32_i32_e32 v71, v71
	v_cvt_f32_i32_e32 v64, v64
	v_cvt_f32_i32_e32 v65, v65
	v_cvt_f32_i32_e32 v66, v66
	v_cvt_f32_i32_e32 v67, v67
	v_cvt_f32_i32_e32 v60, v60
	v_cvt_f32_i32_e32 v61, v61
	v_cvt_f32_i32_e32 v62, v62
	v_cvt_f32_i32_e32 v63, v63
	v_cvt_f32_i32_e32 v56, v56
	v_cvt_f32_i32_e32 v57, v57
	v_cvt_f32_i32_e32 v58, v58
	v_cvt_f32_i32_e32 v59, v59
	v_cvt_f32_i32_e32 v52, v52
	v_cvt_f32_i32_e32 v53, v53
	v_cvt_f32_i32_e32 v54, v54
	v_cvt_f32_i32_e32 v55, v55
	v_cvt_f32_i32_e32 v48, v48
	v_cvt_f32_i32_e32 v49, v49
	v_cvt_f32_i32_e32 v50, v50
	v_cvt_f32_i32_e32 v51, v51
	v_cvt_f32_i32_e32 v40, v40
	v_cvt_f32_i32_e32 v41, v41
	v_cvt_f32_i32_e32 v42, v42
	v_cvt_f32_i32_e32 v43, v43
	v_cvt_f32_i32_e32 v32, v32
	v_cvt_f32_i32_e32 v33, v33
	v_cvt_f32_i32_e32 v34, v34
	v_cvt_f32_i32_e32 v35, v35
	v_cvt_f32_i32_e32 v28, v28
	v_cvt_f32_i32_e32 v29, v29
	v_cvt_f32_i32_e32 v30, v30
	v_cvt_f32_i32_e32 v31, v31
	v_cvt_f32_i32_e32 v24, v24
	v_cvt_f32_i32_e32 v25, v25
	v_cvt_f32_i32_e32 v26, v26
	v_cvt_f32_i32_e32 v27, v27
	v_cvt_f32_i32_e32 v20, v20
	v_cvt_f32_i32_e32 v21, v21
	v_cvt_f32_i32_e32 v22, v22
	v_cvt_f32_i32_e32 v23, v23
	v_cvt_f32_i32_e32 v16, v16
	v_cvt_f32_i32_e32 v17, v17
	v_cvt_f32_i32_e32 v18, v18
	v_cvt_f32_i32_e32 v19, v19
	v_cvt_f32_i32_e32 v12, v12
	v_cvt_f32_i32_e32 v13, v13
	v_cvt_f32_i32_e32 v14, v14
	v_cvt_f32_i32_e32 v15, v15
	v_cvt_f32_i32_e32 v8, v8
	v_cvt_f32_i32_e32 v9, v9
	v_cvt_f32_i32_e32 v10, v10
	v_cvt_f32_i32_e32 v11, v11
	v_cvt_f32_i32_e32 v4, v4
	v_cvt_f32_i32_e32 v5, v5
	v_cvt_f32_i32_e32 v6, v6
	v_cvt_f32_i32_e32 v7, v7
	s_waitcnt vmcnt(0)
; __device__ __forceinline__ unsigned cvt_pk_bf16(float lo, float hi) { unsigned r; asm volatile("v_cvt_pk_bf16_f32 %0, %1, %2" : "=v"(r) : "v"(lo), "v"(hi)); return r; }
; __device__ __forceinline__ float fast_sigmoid(float x) { return __builtin_amdgcn_rcpf(1.0f + __expf(-x)); }
;     __device__ __forceinline__ void operator()(const i32x4 (&acc)[2][2][4][2], const Unit& u, int wr, int wc, int fr, int fq) const {
;     ...
;         for (int ai = 0; ai < 2; ++ai)
; #pragma unroll
;             for (int m = 0; m < 4; ++m) { const int row = row0 + ai * HALF + m * 16; const float ra = rav[ai][m]; bf16_t* rowp = H + (size_t)row * ldh + col0;
;                 float hv[8];
; #pragma unroll
;                 for (int j = 0; j < 4; ++j) { const float g0 = (float)acc[ai][0][m][0][j] * ra * dg0[j], u0 = (float)acc[ai][1][m][0][j] * ra * du0[j]; hv[j] = g0 * fast_sigmoid(g0) * u0;
;                     const float g1 = (float)acc[ai][0][m][1][j] * ra * dg1[j], u1 = (float)acc[ai][1][m][1][j] * ra * du1[j]; hv[4 + j] = g1 * fast_sigmoid(g1) * u1; }
;                 u32x4 w; w.x = cvt_pk_bf16(hv[0], hv[1]); w.y = cvt_pk_bf16(hv[2], hv[3]); w.z = cvt_pk_bf16(hv[4], hv[5]); w.w = cvt_pk_bf16(hv[6], hv[7]);
;                 *(u32x4*)rowp = w; }
	v_pk_mul_f32 v[136:137], v[188:189], v[136:137] op_sel_hi:[0,1]
	v_pk_mul_f32 v[132:133], v[188:189], v[132:133] op_sel_hi:[0,1]
	v_pk_mul_f32 v[138:139], v[188:189], v[138:139] op_sel_hi:[0,1]
	v_pk_mul_f32 v[134:135], v[188:189], v[134:135] op_sel_hi:[0,1]
	v_pk_mul_f32 v[128:129], v[188:189], v[128:129] op_sel_hi:[0,1]
	v_pk_mul_f32 v[124:125], v[188:189], v[124:125] op_sel_hi:[0,1]
	v_pk_mul_f32 v[130:131], v[188:189], v[130:131] op_sel_hi:[0,1]
	v_pk_mul_f32 v[126:127], v[188:189], v[126:127] op_sel_hi:[0,1]
	v_pk_mul_f32 v[136:137], v[44:45], v[136:137]
	v_pk_mul_f32 v[132:133], v[144:145], v[132:133]
	v_pk_mul_f32 v[138:139], v[46:47], v[138:139]
	v_pk_mul_f32 v[134:135], v[146:147], v[134:135]
	v_pk_mul_f32 v[128:129], v[36:37], v[128:129]
	v_pk_mul_f32 v[124:125], v[140:141], v[124:125]
	v_pk_mul_f32 v[130:131], v[38:39], v[130:131]
	v_pk_mul_f32 v[126:127], v[142:143], v[126:127]
	v_pk_mul_f32 v[160:161], v[178:179], v[136:137] op_sel_hi:[0,1]
	v_pk_mul_f32 v[162:163], v[178:179], v[138:139] op_sel_hi:[0,1]
	v_exp_f32_e32 v160, v160
	v_exp_f32_e32 v161, v161
	v_exp_f32_e32 v162, v162
	v_exp_f32_e32 v163, v163
	v_pk_add_f32 v[160:161], v[178:179], v[160:161] op_sel:[1,0] op_sel_hi:[1,1]
	v_pk_add_f32 v[162:163], v[178:179], v[162:163] op_sel:[1,0] op_sel_hi:[1,1]
	v_rcp_f32_e32 v160, v160
	v_rcp_f32_e32 v161, v161
	v_rcp_f32_e32 v162, v162
	v_rcp_f32_e32 v163, v163
	v_pk_mul_f32 v[136:137], v[136:137], v[160:161]
	v_pk_mul_f32 v[138:139], v[138:139], v[162:163]
	v_pk_mul_f32 v[136:137], v[132:133], v[136:137]
	v_pk_mul_f32 v[138:139], v[134:135], v[138:139]
	v_pk_mul_f32 v[160:161], v[178:179], v[128:129] op_sel_hi:[0,1]
	v_pk_mul_f32 v[162:163], v[178:179], v[130:131] op_sel_hi:[0,1]
	v_exp_f32_e32 v160, v160
	v_exp_f32_e32 v161, v161
	v_exp_f32_e32 v162, v162
	v_exp_f32_e32 v163, v163
	v_pk_add_f32 v[160:161], v[178:179], v[160:161] op_sel:[1,0] op_sel_hi:[1,1]
	v_pk_add_f32 v[162:163], v[178:179], v[162:163] op_sel:[1,0] op_sel_hi:[1,1]
	v_rcp_f32_e32 v160, v160
	v_rcp_f32_e32 v161, v161
	v_rcp_f32_e32 v162, v162
	v_rcp_f32_e32 v163, v163
	v_pk_mul_f32 v[128:129], v[128:129], v[160:161]
	v_pk_mul_f32 v[130:131], v[130:131], v[162:163]
	v_pk_mul_f32 v[128:129], v[124:125], v[128:129]
	v_pk_mul_f32 v[130:131], v[126:127], v[130:131]
	v_cvt_pk_bf16_f32 v136, v136, v137
	v_cvt_pk_bf16_f32 v137, v138, v139
	v_cvt_pk_bf16_f32 v138, v128, v129
	v_cvt_pk_bf16_f32 v139, v130, v131
	global_store_dwordx4 v186, v[136:139], s[14:15]
	v_pk_mul_f32 v[120:121], v[180:181], v[120:121] op_sel_hi:[0,1]
	v_pk_mul_f32 v[116:117], v[180:181], v[116:117] op_sel_hi:[0,1]
	v_pk_mul_f32 v[122:123], v[180:181], v[122:123] op_sel_hi:[0,1]
	v_pk_mul_f32 v[118:119], v[180:181], v[118:119] op_sel_hi:[0,1]
	v_pk_mul_f32 v[112:113], v[180:181], v[112:113] op_sel_hi:[0,1]
	v_pk_mul_f32 v[108:109], v[180:181], v[108:109] op_sel_hi:[0,1]
	v_pk_mul_f32 v[114:115], v[180:181], v[114:115] op_sel_hi:[0,1]
	v_pk_mul_f32 v[110:111], v[180:181], v[110:111] op_sel_hi:[0,1]
	v_pk_mul_f32 v[120:121], v[44:45], v[120:121]
	v_pk_mul_f32 v[116:117], v[144:145], v[116:117]
	v_pk_mul_f32 v[122:123], v[46:47], v[122:123]
	v_pk_mul_f32 v[118:119], v[146:147], v[118:119]
	v_pk_mul_f32 v[112:113], v[36:37], v[112:113]
	v_pk_mul_f32 v[108:109], v[140:141], v[108:109]
	v_pk_mul_f32 v[114:115], v[38:39], v[114:115]
	v_pk_mul_f32 v[110:111], v[142:143], v[110:111]
	v_pk_mul_f32 v[160:161], v[178:179], v[120:121] op_sel_hi:[0,1]
	v_pk_mul_f32 v[162:163], v[178:179], v[122:123] op_sel_hi:[0,1]
	v_exp_f32_e32 v160, v160
	v_exp_f32_e32 v161, v161
	v_exp_f32_e32 v162, v162
	v_exp_f32_e32 v163, v163
	v_pk_add_f32 v[160:161], v[178:179], v[160:161] op_sel:[1,0] op_sel_hi:[1,1]
	v_pk_add_f32 v[162:163], v[178:179], v[162:163] op_sel:[1,0] op_sel_hi:[1,1]
	v_rcp_f32_e32 v160, v160
	v_rcp_f32_e32 v161, v161
	v_rcp_f32_e32 v162, v162
	v_rcp_f32_e32 v163, v163
	v_pk_mul_f32 v[120:121], v[120:121], v[160:161]
	v_pk_mul_f32 v[122:123], v[122:123], v[162:163]
	v_pk_mul_f32 v[120:121], v[116:117], v[120:121]
	v_pk_mul_f32 v[122:123], v[118:119], v[122:123]
	v_pk_mul_f32 v[160:161], v[178:179], v[112:113] op_sel_hi:[0,1]
	v_pk_mul_f32 v[162:163], v[178:179], v[114:115] op_sel_hi:[0,1]
	v_exp_f32_e32 v160, v160
	v_exp_f32_e32 v161, v161
	v_exp_f32_e32 v162, v162
	v_exp_f32_e32 v163, v163
	v_pk_add_f32 v[160:161], v[178:179], v[160:161] op_sel:[1,0] op_sel_hi:[1,1]
	v_pk_add_f32 v[162:163], v[178:179], v[162:163] op_sel:[1,0] op_sel_hi:[1,1]
	v_rcp_f32_e32 v160, v160
	v_rcp_f32_e32 v161, v161
	v_rcp_f32_e32 v162, v162
	v_rcp_f32_e32 v163, v163
	v_pk_mul_f32 v[112:113], v[112:113], v[160:161]
	v_pk_mul_f32 v[114:115], v[114:115], v[162:163]
	v_pk_mul_f32 v[112:113], v[108:109], v[112:113]
	v_pk_mul_f32 v[114:115], v[110:111], v[114:115]
	v_cvt_pk_bf16_f32 v120, v120, v121
	v_cvt_pk_bf16_f32 v121, v122, v123
	v_cvt_pk_bf16_f32 v122, v112, v113
	v_cvt_pk_bf16_f32 v123, v114, v115
	v_add_u32_e32 v187, 0x56000, v186
	global_store_dwordx4 v187, v[120:123], s[14:15]
	v_pk_mul_f32 v[104:105], v[176:177], v[104:105] op_sel_hi:[0,1]
	v_pk_mul_f32 v[100:101], v[176:177], v[100:101] op_sel_hi:[0,1]
	v_pk_mul_f32 v[106:107], v[176:177], v[106:107] op_sel_hi:[0,1]
	v_pk_mul_f32 v[102:103], v[176:177], v[102:103] op_sel_hi:[0,1]
	v_pk_mul_f32 v[96:97], v[176:177], v[96:97] op_sel_hi:[0,1]
	v_pk_mul_f32 v[92:93], v[176:177], v[92:93] op_sel_hi:[0,1]
	v_pk_mul_f32 v[98:99], v[176:177], v[98:99] op_sel_hi:[0,1]
	v_pk_mul_f32 v[94:95], v[176:177], v[94:95] op_sel_hi:[0,1]
	v_pk_mul_f32 v[104:105], v[44:45], v[104:105]
	v_pk_mul_f32 v[100:101], v[144:145], v[100:101]
	v_pk_mul_f32 v[106:107], v[46:47], v[106:107]
; __device__ __forceinline__ unsigned cvt_pk_bf16(float lo, float hi) { unsigned r; asm volatile("v_cvt_pk_bf16_f32 %0, %1, %2" : "=v"(r) : "v"(lo), "v"(hi)); return r; }
; __device__ __forceinline__ float fast_sigmoid(float x) { return __builtin_amdgcn_rcpf(1.0f + __expf(-x)); }
;     __device__ __forceinline__ void operator()(const i32x4 (&acc)[2][2][4][2], const Unit& u, int wr, int wc, int fr, int fq) const {
;     ...
;         for (int ai = 0; ai < 2; ++ai)
; #pragma unroll
;             for (int m = 0; m < 4; ++m) { const int row = row0 + ai * HALF + m * 16; const float ra = rav[ai][m]; bf16_t* rowp = H + (size_t)row * ldh + col0;
;                 float hv[8];
; #pragma unroll
;                 for (int j = 0; j < 4; ++j) { const float g0 = (float)acc[ai][0][m][0][j] * ra * dg0[j], u0 = (float)acc[ai][1][m][0][j] * ra * du0[j]; hv[j] = g0 * fast_sigmoid(g0) * u0;
;                     const float g1 = (float)acc[ai][0][m][1][j] * ra * dg1[j], u1 = (float)acc[ai][1][m][1][j] * ra * du1[j]; hv[4 + j] = g1 * fast_sigmoid(g1) * u1; }
;                 u32x4 w; w.x = cvt_pk_bf16(hv[0], hv[1]); w.y = cvt_pk_bf16(hv[2], hv[3]); w.z = cvt_pk_bf16(hv[4], hv[5]); w.w = cvt_pk_bf16(hv[6], hv[7]);
;                 *(u32x4*)rowp = w; }
	v_pk_mul_f32 v[102:103], v[146:147], v[102:103]
	v_pk_mul_f32 v[96:97], v[36:37], v[96:97]
	v_pk_mul_f32 v[92:93], v[140:141], v[92:93]
	v_pk_mul_f32 v[98:99], v[38:39], v[98:99]
	v_pk_mul_f32 v[94:95], v[142:143], v[94:95]
	v_pk_mul_f32 v[160:161], v[178:179], v[104:105] op_sel_hi:[0,1]
	v_pk_mul_f32 v[162:163], v[178:179], v[106:107] op_sel_hi:[0,1]
	v_exp_f32_e32 v160, v160
	v_exp_f32_e32 v161, v161
	v_exp_f32_e32 v162, v162
	v_exp_f32_e32 v163, v163
	v_pk_add_f32 v[160:161], v[178:179], v[160:161] op_sel:[1,0] op_sel_hi:[1,1]
	v_pk_add_f32 v[162:163], v[178:179], v[162:163] op_sel:[1,0] op_sel_hi:[1,1]
	v_rcp_f32_e32 v160, v160
	v_rcp_f32_e32 v161, v161
	v_rcp_f32_e32 v162, v162
	v_rcp_f32_e32 v163, v163
	v_pk_mul_f32 v[104:105], v[104:105], v[160:161]
	v_pk_mul_f32 v[106:107], v[106:107], v[162:163]
	v_pk_mul_f32 v[104:105], v[100:101], v[104:105]
	v_pk_mul_f32 v[106:107], v[102:103], v[106:107]
	v_pk_mul_f32 v[160:161], v[178:179], v[96:97] op_sel_hi:[0,1]
	v_pk_mul_f32 v[162:163], v[178:179], v[98:99] op_sel_hi:[0,1]
	v_exp_f32_e32 v160, v160
	v_exp_f32_e32 v161, v161
	v_exp_f32_e32 v162, v162
	v_exp_f32_e32 v163, v163
	v_pk_add_f32 v[160:161], v[178:179], v[160:161] op_sel:[1,0] op_sel_hi:[1,1]
	v_pk_add_f32 v[162:163], v[178:179], v[162:163] op_sel:[1,0] op_sel_hi:[1,1]
	v_rcp_f32_e32 v160, v160
	v_rcp_f32_e32 v161, v161
	v_rcp_f32_e32 v162, v162
	v_rcp_f32_e32 v163, v163
	v_pk_mul_f32 v[96:97], v[96:97], v[160:161]
	v_pk_mul_f32 v[98:99], v[98:99], v[162:163]
	v_pk_mul_f32 v[96:97], v[92:93], v[96:97]
	v_pk_mul_f32 v[98:99], v[94:95], v[98:99]
	v_cvt_pk_bf16_f32 v104, v104, v105
	v_cvt_pk_bf16_f32 v105, v106, v107
	v_cvt_pk_bf16_f32 v106, v96, v97
	v_cvt_pk_bf16_f32 v107, v98, v99
	v_add_u32_e32 v187, 0xac000, v186
	global_store_dwordx4 v187, v[104:107], s[14:15]
	v_pk_mul_f32 v[88:89], v[172:173], v[88:89] op_sel_hi:[0,1]
	v_pk_mul_f32 v[84:85], v[172:173], v[84:85] op_sel_hi:[0,1]
	v_pk_mul_f32 v[90:91], v[172:173], v[90:91] op_sel_hi:[0,1]
	v_pk_mul_f32 v[86:87], v[172:173], v[86:87] op_sel_hi:[0,1]
	v_pk_mul_f32 v[80:81], v[172:173], v[80:81] op_sel_hi:[0,1]
	v_pk_mul_f32 v[76:77], v[172:173], v[76:77] op_sel_hi:[0,1]
	v_pk_mul_f32 v[82:83], v[172:173], v[82:83] op_sel_hi:[0,1]
	v_pk_mul_f32 v[78:79], v[172:173], v[78:79] op_sel_hi:[0,1]
	v_pk_mul_f32 v[88:89], v[44:45], v[88:89]
	v_pk_mul_f32 v[84:85], v[144:145], v[84:85]
	v_pk_mul_f32 v[90:91], v[46:47], v[90:91]
	v_pk_mul_f32 v[86:87], v[146:147], v[86:87]
	v_pk_mul_f32 v[80:81], v[36:37], v[80:81]
	v_pk_mul_f32 v[76:77], v[140:141], v[76:77]
	v_pk_mul_f32 v[82:83], v[38:39], v[82:83]
	v_pk_mul_f32 v[78:79], v[142:143], v[78:79]
	v_pk_mul_f32 v[160:161], v[178:179], v[88:89] op_sel_hi:[0,1]
	v_pk_mul_f32 v[162:163], v[178:179], v[90:91] op_sel_hi:[0,1]
	v_exp_f32_e32 v160, v160
	v_exp_f32_e32 v161, v161
	v_exp_f32_e32 v162, v162
	v_exp_f32_e32 v163, v163
	v_pk_add_f32 v[160:161], v[178:179], v[160:161] op_sel:[1,0] op_sel_hi:[1,1]
	v_pk_add_f32 v[162:163], v[178:179], v[162:163] op_sel:[1,0] op_sel_hi:[1,1]
	v_rcp_f32_e32 v160, v160
	v_rcp_f32_e32 v161, v161
	v_rcp_f32_e32 v162, v162
	v_rcp_f32_e32 v163, v163
	v_pk_mul_f32 v[88:89], v[88:89], v[160:161]
	v_pk_mul_f32 v[90:91], v[90:91], v[162:163]
	v_pk_mul_f32 v[88:89], v[84:85], v[88:89]
	v_pk_mul_f32 v[90:91], v[86:87], v[90:91]
	v_pk_mul_f32 v[160:161], v[178:179], v[80:81] op_sel_hi:[0,1]
	v_pk_mul_f32 v[162:163], v[178:179], v[82:83] op_sel_hi:[0,1]
	v_exp_f32_e32 v160, v160
	v_exp_f32_e32 v161, v161
	v_exp_f32_e32 v162, v162
	v_exp_f32_e32 v163, v163
	v_pk_add_f32 v[160:161], v[178:179], v[160:161] op_sel:[1,0] op_sel_hi:[1,1]
	v_pk_add_f32 v[162:163], v[178:179], v[162:163] op_sel:[1,0] op_sel_hi:[1,1]
	v_rcp_f32_e32 v160, v160
	v_rcp_f32_e32 v161, v161
	v_rcp_f32_e32 v162, v162
	v_rcp_f32_e32 v163, v163
	v_pk_mul_f32 v[80:81], v[80:81], v[160:161]
	v_pk_mul_f32 v[82:83], v[82:83], v[162:163]
	v_pk_mul_f32 v[80:81], v[76:77], v[80:81]
	v_pk_mul_f32 v[82:83], v[78:79], v[82:83]
	v_cvt_pk_bf16_f32 v88, v88, v89
	v_cvt_pk_bf16_f32 v89, v90, v91
	v_cvt_pk_bf16_f32 v90, v80, v81
	v_cvt_pk_bf16_f32 v91, v82, v83
	v_add_u32_e32 v187, 0x102000, v186
	global_store_dwordx4 v187, v[88:91], s[14:15]
	v_pk_mul_f32 v[72:73], v[170:171], v[72:73] op_sel_hi:[0,1]
	v_pk_mul_f32 v[68:69], v[170:171], v[68:69] op_sel_hi:[0,1]
	v_pk_mul_f32 v[74:75], v[170:171], v[74:75] op_sel_hi:[0,1]
	v_pk_mul_f32 v[70:71], v[170:171], v[70:71] op_sel_hi:[0,1]
	v_pk_mul_f32 v[64:65], v[170:171], v[64:65] op_sel_hi:[0,1]
	v_pk_mul_f32 v[60:61], v[170:171], v[60:61] op_sel_hi:[0,1]
	v_pk_mul_f32 v[66:67], v[170:171], v[66:67] op_sel_hi:[0,1]
	v_pk_mul_f32 v[62:63], v[170:171], v[62:63] op_sel_hi:[0,1]
	v_pk_mul_f32 v[72:73], v[44:45], v[72:73]
	v_pk_mul_f32 v[68:69], v[144:145], v[68:69]
	v_pk_mul_f32 v[74:75], v[46:47], v[74:75]
	v_pk_mul_f32 v[70:71], v[146:147], v[70:71]
	v_pk_mul_f32 v[64:65], v[36:37], v[64:65]
	v_pk_mul_f32 v[60:61], v[140:141], v[60:61]
	v_pk_mul_f32 v[66:67], v[38:39], v[66:67]
	v_pk_mul_f32 v[62:63], v[142:143], v[62:63]
	v_pk_mul_f32 v[160:161], v[178:179], v[72:73] op_sel_hi:[0,1]
	v_pk_mul_f32 v[162:163], v[178:179], v[74:75] op_sel_hi:[0,1]
	v_exp_f32_e32 v160, v160
	v_exp_f32_e32 v161, v161
	v_exp_f32_e32 v162, v162
	v_exp_f32_e32 v163, v163
	v_pk_add_f32 v[160:161], v[178:179], v[160:161] op_sel:[1,0] op_sel_hi:[1,1]
	v_pk_add_f32 v[162:163], v[178:179], v[162:163] op_sel:[1,0] op_sel_hi:[1,1]
	v_rcp_f32_e32 v160, v160
	v_rcp_f32_e32 v161, v161
	v_rcp_f32_e32 v162, v162
	v_rcp_f32_e32 v163, v163
	v_pk_mul_f32 v[72:73], v[72:73], v[160:161]
	v_pk_mul_f32 v[74:75], v[74:75], v[162:163]
	v_pk_mul_f32 v[72:73], v[68:69], v[72:73]
; __device__ __forceinline__ unsigned cvt_pk_bf16(float lo, float hi) { unsigned r; asm volatile("v_cvt_pk_bf16_f32 %0, %1, %2" : "=v"(r) : "v"(lo), "v"(hi)); return r; }
; __device__ __forceinline__ float fast_sigmoid(float x) { return __builtin_amdgcn_rcpf(1.0f + __expf(-x)); }
;     __device__ __forceinline__ void operator()(const i32x4 (&acc)[2][2][4][2], const Unit& u, int wr, int wc, int fr, int fq) const {
;     ...
;         for (int ai = 0; ai < 2; ++ai)
; #pragma unroll
;             for (int m = 0; m < 4; ++m) { const int row = row0 + ai * HALF + m * 16; const float ra = rav[ai][m]; bf16_t* rowp = H + (size_t)row * ldh + col0;
;                 float hv[8];
; #pragma unroll
;                 for (int j = 0; j < 4; ++j) { const float g0 = (float)acc[ai][0][m][0][j] * ra * dg0[j], u0 = (float)acc[ai][1][m][0][j] * ra * du0[j]; hv[j] = g0 * fast_sigmoid(g0) * u0;
;                     const float g1 = (float)acc[ai][0][m][1][j] * ra * dg1[j], u1 = (float)acc[ai][1][m][1][j] * ra * du1[j]; hv[4 + j] = g1 * fast_sigmoid(g1) * u1; }
;                 u32x4 w; w.x = cvt_pk_bf16(hv[0], hv[1]); w.y = cvt_pk_bf16(hv[2], hv[3]); w.z = cvt_pk_bf16(hv[4], hv[5]); w.w = cvt_pk_bf16(hv[6], hv[7]);
;                 *(u32x4*)rowp = w; }
	v_pk_mul_f32 v[74:75], v[70:71], v[74:75]
	v_pk_mul_f32 v[160:161], v[178:179], v[64:65] op_sel_hi:[0,1]
	v_pk_mul_f32 v[162:163], v[178:179], v[66:67] op_sel_hi:[0,1]
	v_exp_f32_e32 v160, v160
	v_exp_f32_e32 v161, v161
	v_exp_f32_e32 v162, v162
	v_exp_f32_e32 v163, v163
	v_pk_add_f32 v[160:161], v[178:179], v[160:161] op_sel:[1,0] op_sel_hi:[1,1]
	v_pk_add_f32 v[162:163], v[178:179], v[162:163] op_sel:[1,0] op_sel_hi:[1,1]
	v_rcp_f32_e32 v160, v160
	v_rcp_f32_e32 v161, v161
	v_rcp_f32_e32 v162, v162
	v_rcp_f32_e32 v163, v163
	v_pk_mul_f32 v[64:65], v[64:65], v[160:161]
	v_pk_mul_f32 v[66:67], v[66:67], v[162:163]
	v_pk_mul_f32 v[64:65], v[60:61], v[64:65]
	v_pk_mul_f32 v[66:67], v[62:63], v[66:67]
	v_cvt_pk_bf16_f32 v72, v72, v73
	v_cvt_pk_bf16_f32 v73, v74, v75
	v_cvt_pk_bf16_f32 v74, v64, v65
	v_cvt_pk_bf16_f32 v75, v66, v67
	v_add_u32_e32 v187, 0x2b0000, v186
	global_store_dwordx4 v187, v[72:75], s[14:15]
	v_pk_mul_f32 v[56:57], v[168:169], v[56:57] op_sel_hi:[0,1]
	v_pk_mul_f32 v[52:53], v[168:169], v[52:53] op_sel_hi:[0,1]
	v_pk_mul_f32 v[58:59], v[168:169], v[58:59] op_sel_hi:[0,1]
	v_pk_mul_f32 v[54:55], v[168:169], v[54:55] op_sel_hi:[0,1]
	v_pk_mul_f32 v[48:49], v[168:169], v[48:49] op_sel_hi:[0,1]
	v_pk_mul_f32 v[40:41], v[168:169], v[40:41] op_sel_hi:[0,1]
	v_pk_mul_f32 v[50:51], v[168:169], v[50:51] op_sel_hi:[0,1]
	v_pk_mul_f32 v[42:43], v[168:169], v[42:43] op_sel_hi:[0,1]
	v_pk_mul_f32 v[56:57], v[44:45], v[56:57]
	v_pk_mul_f32 v[52:53], v[144:145], v[52:53]
	v_pk_mul_f32 v[58:59], v[46:47], v[58:59]
	v_pk_mul_f32 v[54:55], v[146:147], v[54:55]
	v_pk_mul_f32 v[48:49], v[36:37], v[48:49]
	v_pk_mul_f32 v[40:41], v[140:141], v[40:41]
	v_pk_mul_f32 v[50:51], v[38:39], v[50:51]
	v_pk_mul_f32 v[42:43], v[142:143], v[42:43]
	v_pk_mul_f32 v[160:161], v[178:179], v[56:57] op_sel_hi:[0,1]
	v_pk_mul_f32 v[162:163], v[178:179], v[58:59] op_sel_hi:[0,1]
	v_exp_f32_e32 v160, v160
	v_exp_f32_e32 v161, v161
	v_exp_f32_e32 v162, v162
	v_exp_f32_e32 v163, v163
	v_pk_add_f32 v[160:161], v[178:179], v[160:161] op_sel:[1,0] op_sel_hi:[1,1]
	v_pk_add_f32 v[162:163], v[178:179], v[162:163] op_sel:[1,0] op_sel_hi:[1,1]
	v_rcp_f32_e32 v160, v160
	v_rcp_f32_e32 v161, v161
	v_rcp_f32_e32 v162, v162
	v_rcp_f32_e32 v163, v163
	v_pk_mul_f32 v[56:57], v[56:57], v[160:161]
	v_pk_mul_f32 v[58:59], v[58:59], v[162:163]
	v_pk_mul_f32 v[56:57], v[52:53], v[56:57]
	v_pk_mul_f32 v[58:59], v[54:55], v[58:59]
	v_pk_mul_f32 v[160:161], v[178:179], v[48:49] op_sel_hi:[0,1]
	v_pk_mul_f32 v[162:163], v[178:179], v[50:51] op_sel_hi:[0,1]
	v_exp_f32_e32 v160, v160
	v_exp_f32_e32 v161, v161
	v_exp_f32_e32 v162, v162
	v_exp_f32_e32 v163, v163
	v_pk_add_f32 v[160:161], v[178:179], v[160:161] op_sel:[1,0] op_sel_hi:[1,1]
	v_pk_add_f32 v[162:163], v[178:179], v[162:163] op_sel:[1,0] op_sel_hi:[1,1]
	v_rcp_f32_e32 v160, v160
	v_rcp_f32_e32 v161, v161
	v_rcp_f32_e32 v162, v162
	v_rcp_f32_e32 v163, v163
	v_pk_mul_f32 v[48:49], v[48:49], v[160:161]
	v_pk_mul_f32 v[50:51], v[50:51], v[162:163]
	v_pk_mul_f32 v[48:49], v[40:41], v[48:49]
	v_pk_mul_f32 v[50:51], v[42:43], v[50:51]
	v_cvt_pk_bf16_f32 v56, v56, v57
	v_cvt_pk_bf16_f32 v57, v58, v59
	v_cvt_pk_bf16_f32 v58, v48, v49
	v_cvt_pk_bf16_f32 v59, v50, v51
	v_add_u32_e32 v187, 0x306000, v186
	global_store_dwordx4 v187, v[56:59], s[14:15]
	v_pk_mul_f32 v[32:33], v[166:167], v[32:33] op_sel_hi:[0,1]
	v_pk_mul_f32 v[28:29], v[166:167], v[28:29] op_sel_hi:[0,1]
	v_pk_mul_f32 v[34:35], v[166:167], v[34:35] op_sel_hi:[0,1]
	v_pk_mul_f32 v[30:31], v[166:167], v[30:31] op_sel_hi:[0,1]
	v_pk_mul_f32 v[24:25], v[166:167], v[24:25] op_sel_hi:[0,1]
	v_pk_mul_f32 v[20:21], v[166:167], v[20:21] op_sel_hi:[0,1]
	v_pk_mul_f32 v[26:27], v[166:167], v[26:27] op_sel_hi:[0,1]
	v_pk_mul_f32 v[22:23], v[166:167], v[22:23] op_sel_hi:[0,1]
	v_pk_mul_f32 v[32:33], v[44:45], v[32:33]
	v_pk_mul_f32 v[28:29], v[144:145], v[28:29]
	v_pk_mul_f32 v[34:35], v[46:47], v[34:35]
	v_pk_mul_f32 v[30:31], v[146:147], v[30:31]
	v_pk_mul_f32 v[24:25], v[36:37], v[24:25]
	v_pk_mul_f32 v[20:21], v[140:141], v[20:21]
	v_pk_mul_f32 v[26:27], v[38:39], v[26:27]
; __device__ __forceinline__ unsigned cvt_pk_bf16(float lo, float hi) { unsigned r; asm volatile("v_cvt_pk_bf16_f32 %0, %1, %2" : "=v"(r) : "v"(lo), "v"(hi)); return r; }
; __device__ __forceinline__ float fast_sigmoid(float x) { return __builtin_amdgcn_rcpf(1.0f + __expf(-x)); }
;     __device__ __forceinline__ void operator()(const i32x4 (&acc)[2][2][4][2], const Unit& u, int wr, int wc, int fr, int fq) const {
;     ...
;         for (int ai = 0; ai < 2; ++ai)
; #pragma unroll
;             for (int m = 0; m < 4; ++m) { const int row = row0 + ai * HALF + m * 16; const float ra = rav[ai][m]; bf16_t* rowp = H + (size_t)row * ldh + col0;
;                 float hv[8];
; #pragma unroll
;                 for (int j = 0; j < 4; ++j) { const float g0 = (float)acc[ai][0][m][0][j] * ra * dg0[j], u0 = (float)acc[ai][1][m][0][j] * ra * du0[j]; hv[j] = g0 * fast_sigmoid(g0) * u0;
;                     const float g1 = (float)acc[ai][0][m][1][j] * ra * dg1[j], u1 = (float)acc[ai][1][m][1][j] * ra * du1[j]; hv[4 + j] = g1 * fast_sigmoid(g1) * u1; }
;                 u32x4 w; w.x = cvt_pk_bf16(hv[0], hv[1]); w.y = cvt_pk_bf16(hv[2], hv[3]); w.z = cvt_pk_bf16(hv[4], hv[5]); w.w = cvt_pk_bf16(hv[6], hv[7]);
;                 *(u32x4*)rowp = w; }
	v_pk_mul_f32 v[22:23], v[142:143], v[22:23]
	v_pk_mul_f32 v[160:161], v[178:179], v[32:33] op_sel_hi:[0,1]
	v_pk_mul_f32 v[162:163], v[178:179], v[34:35] op_sel_hi:[0,1]
	v_exp_f32_e32 v160, v160
	v_exp_f32_e32 v161, v161
	v_exp_f32_e32 v162, v162
	v_exp_f32_e32 v163, v163
	v_pk_add_f32 v[160:161], v[178:179], v[160:161] op_sel:[1,0] op_sel_hi:[1,1]
	v_pk_add_f32 v[162:163], v[178:179], v[162:163] op_sel:[1,0] op_sel_hi:[1,1]
	v_rcp_f32_e32 v160, v160
	v_rcp_f32_e32 v161, v161
	v_rcp_f32_e32 v162, v162
	v_rcp_f32_e32 v163, v163
	v_pk_mul_f32 v[32:33], v[32:33], v[160:161]
	v_pk_mul_f32 v[34:35], v[34:35], v[162:163]
	v_pk_mul_f32 v[32:33], v[28:29], v[32:33]
	v_pk_mul_f32 v[34:35], v[30:31], v[34:35]
	v_pk_mul_f32 v[160:161], v[178:179], v[24:25] op_sel_hi:[0,1]
	v_pk_mul_f32 v[162:163], v[178:179], v[26:27] op_sel_hi:[0,1]
	v_exp_f32_e32 v160, v160
	v_exp_f32_e32 v161, v161
	v_exp_f32_e32 v162, v162
	v_exp_f32_e32 v163, v163
	v_pk_add_f32 v[160:161], v[178:179], v[160:161] op_sel:[1,0] op_sel_hi:[1,1]
	v_pk_add_f32 v[162:163], v[178:179], v[162:163] op_sel:[1,0] op_sel_hi:[1,1]
	v_rcp_f32_e32 v160, v160
	v_rcp_f32_e32 v161, v161
	v_rcp_f32_e32 v162, v162
	v_rcp_f32_e32 v163, v163
	v_pk_mul_f32 v[24:25], v[24:25], v[160:161]
	v_pk_mul_f32 v[26:27], v[26:27], v[162:163]
	v_pk_mul_f32 v[24:25], v[20:21], v[24:25]
	v_pk_mul_f32 v[26:27], v[22:23], v[26:27]
	v_cvt_pk_bf16_f32 v32, v32, v33
	v_cvt_pk_bf16_f32 v33, v34, v35
	v_cvt_pk_bf16_f32 v34, v24, v25
	v_cvt_pk_bf16_f32 v35, v26, v27
	v_add_u32_e32 v187, 0x35c000, v186
	global_store_dwordx4 v187, v[32:35], s[14:15]
	v_pk_mul_f32 v[16:17], v[158:159], v[16:17] op_sel_hi:[0,1]
	v_pk_mul_f32 v[12:13], v[158:159], v[12:13] op_sel_hi:[0,1]
	v_pk_mul_f32 v[18:19], v[158:159], v[18:19] op_sel_hi:[0,1]
	v_pk_mul_f32 v[14:15], v[158:159], v[14:15] op_sel_hi:[0,1]
	v_pk_mul_f32 v[8:9], v[158:159], v[8:9] op_sel_hi:[0,1]
	v_pk_mul_f32 v[4:5], v[158:159], v[4:5] op_sel_hi:[0,1]
	v_pk_mul_f32 v[10:11], v[158:159], v[10:11] op_sel_hi:[0,1]
	v_pk_mul_f32 v[6:7], v[158:159], v[6:7] op_sel_hi:[0,1]
	v_pk_mul_f32 v[16:17], v[44:45], v[16:17]
	v_pk_mul_f32 v[12:13], v[144:145], v[12:13]
	v_pk_mul_f32 v[18:19], v[46:47], v[18:19]
	v_pk_mul_f32 v[14:15], v[146:147], v[14:15]
	v_pk_mul_f32 v[8:9], v[36:37], v[8:9]
	v_pk_mul_f32 v[4:5], v[140:141], v[4:5]
	v_pk_mul_f32 v[10:11], v[38:39], v[10:11]
	v_pk_mul_f32 v[6:7], v[142:143], v[6:7]
	v_pk_mul_f32 v[160:161], v[178:179], v[16:17] op_sel_hi:[0,1]
	v_pk_mul_f32 v[162:163], v[178:179], v[18:19] op_sel_hi:[0,1]
	v_exp_f32_e32 v160, v160
	v_exp_f32_e32 v161, v161
	v_exp_f32_e32 v162, v162
	v_exp_f32_e32 v163, v163
	v_pk_add_f32 v[160:161], v[178:179], v[160:161] op_sel:[1,0] op_sel_hi:[1,1]
	v_pk_add_f32 v[162:163], v[178:179], v[162:163] op_sel:[1,0] op_sel_hi:[1,1]
	v_rcp_f32_e32 v160, v160
	v_rcp_f32_e32 v161, v161
	v_rcp_f32_e32 v162, v162
	v_rcp_f32_e32 v163, v163
	v_pk_mul_f32 v[16:17], v[16:17], v[160:161]
	v_pk_mul_f32 v[18:19], v[18:19], v[162:163]
	v_pk_mul_f32 v[16:17], v[12:13], v[16:17]
	v_pk_mul_f32 v[18:19], v[14:15], v[18:19]
	v_pk_mul_f32 v[160:161], v[178:179], v[8:9] op_sel_hi:[0,1]
	v_pk_mul_f32 v[162:163], v[178:179], v[10:11] op_sel_hi:[0,1]
	v_exp_f32_e32 v160, v160
	v_exp_f32_e32 v161, v161
	v_exp_f32_e32 v162, v162
	v_exp_f32_e32 v163, v163
	v_pk_add_f32 v[160:161], v[178:179], v[160:161] op_sel:[1,0] op_sel_hi:[1,1]
	v_pk_add_f32 v[162:163], v[178:179], v[162:163] op_sel:[1,0] op_sel_hi:[1,1]
	v_rcp_f32_e32 v160, v160
	v_rcp_f32_e32 v161, v161
	v_rcp_f32_e32 v162, v162
	v_rcp_f32_e32 v163, v163
	v_pk_mul_f32 v[8:9], v[8:9], v[160:161]
	v_pk_mul_f32 v[10:11], v[10:11], v[162:163]
	v_pk_mul_f32 v[8:9], v[4:5], v[8:9]
	v_pk_mul_f32 v[10:11], v[6:7], v[10:11]
	v_cvt_pk_bf16_f32 v16, v16, v17
	v_cvt_pk_bf16_f32 v17, v18, v19
	v_cvt_pk_bf16_f32 v18, v8, v9
	v_cvt_pk_bf16_f32 v19, v10, v11
	v_add_u32_e32 v187, 0x3b2000, v186
	global_store_dwordx4 v187, v[16:19], s[14:15]
	s_mov_b32 s67, 0x40000
	s_mov_b64 s[34:35], -1
	s_andn2_b64 vcc, exec, s[10:11]
	s_cbranch_vccnz .LBB0_1587
	s_andn2_b64 vcc, exec, s[12:13]
	s_cbranch_vccnz .LBB0_1586
	s_barrier
	s_branch .LBB0_1586
